# EpiResid sum-of-squares reduction: xor-16/xor-32 lane exchange via v_permlane16/32_swap (VALU) instead of ds_bpermute + wait (16 LDS round trips per unit removed)
# speedup vs baseline: 1.0041x; 1.0041x over previous
; __device__ __forceinline__ unsigned pk_bf16(float lo, float hi) { f32x2e v = {lo, hi}; bf16x2e b = __builtin_convertvector(v, bf16x2e); return __builtin_bit_cast(unsigned, b); }
;     __device__ __forceinline__ void operator()(const f32x4 (&acc)[2][2][4][2], const Unit& u, int wr, int wc, int fr, int fq) const {
;         const int col0 = u.pn * BM + wc * 32 + 8 * fq;
;         bf16_t* base = H + (size_t)(u.pm * BM + wr * 64 + fr) * ldc + col0;
;         u32x4 r[2][4][2];
; #pragma unroll
;         for (int ai = 0; ai < 2; ++ai)
; #pragma unroll
;             for (int m = 0; m < 4; ++m)
; #pragma unroll
;                 for (int bj = 0; bj < 2; ++bj) r[ai][m][bj] = *(const u32x4*)(base + (size_t)(ai * HALF + m * 16) * ldc + bj * HALF);
; #pragma unroll
;         for (int ai = 0; ai < 2; ++ai)
; #pragma unroll
;             for (int m = 0; m < 4; ++m) { const int row = u.pm * BM + ai * HALF + wr * 64 + m * 16 + fr; bf16_t* rowp = base + (size_t)(ai * HALF + m * 16) * ldc;
;                 float qs = 0.f;
; #pragma unroll
;                 for (int bj = 0; bj < 2; ++bj) { const f32x4 a0 = acc[ai][bj][m][0], a1 = acc[ai][bj][m][1]; const u32x4 q = r[ai][m][bj]; u32x4 w;
;                     w.x = pk_bf16(__uint_as_float(q.x << 16) + a0.x, __uint_as_float(q.x & 0xffff0000u) + a0.y);
;                     w.y = pk_bf16(__uint_as_float(q.y << 16) + a0.z, __uint_as_float(q.y & 0xffff0000u) + a0.w);
;                     w.z = pk_bf16(__uint_as_float(q.z << 16) + a1.x, __uint_as_float(q.z & 0xffff0000u) + a1.y);
;                     w.w = pk_bf16(__uint_as_float(q.w << 16) + a1.z, __uint_as_float(q.w & 0xffff0000u) + a1.w);
;                     *(u32x4*)(rowp + bj * HALF) = w;
; #pragma unroll
;                     for (int e = 0; e < 4; ++e) { const float h0 = __uint_as_float(w[e] << 16), h1 = __uint_as_float(w[e] & 0xffff0000u); qs += h0 * h0 + h1 * h1; } }
;                 qs += __shfl_xor(qs, 16); qs += __shfl_xor(qs, 32);
;                 if (fq == 0) ss[(size_t)row * 32 + u.pn * 4 + wc] = qs; }
.LBB0_450:
	v_lshl_add_u32 v212, s7, 8, v231
	v_ashrrev_i32_e32 v213, 31, v212
	v_readlane_b32 s0, v254, 59
	v_lshl_or_b32 v98, s6, 8, v233
	v_lshlrev_b64 v[100:101], 12, v[212:213]
	v_readlane_b32 s1, v254, 60
	v_ashrrev_i32_e32 v99, 31, v98
	v_and_b32_e32 v229, 64, v220
	v_lshl_add_u64 v[100:101], s[0:1], 0, v[100:101]
	v_lshl_add_u64 v[214:215], v[98:99], 1, v[100:101]
	global_load_dwordx4 v[190:193], v[214:215], off
	global_load_dwordx4 v[186:189], v[214:215], off offset:256
	s_mov_b32 s0, 0x10000
	v_add_co_u32_e32 v98, vcc, s0, v214
	s_mov_b32 s0, 0x20000
	s_nop 0
	v_addc_co_u32_e32 v99, vcc, 0, v215, vcc
	global_load_dwordx4 v[182:185], v[98:99], off
	global_load_dwordx4 v[178:181], v[98:99], off offset:256
	v_add_co_u32_e32 v98, vcc, s0, v214
	s_mov_b32 s0, 0x30000
	s_nop 0
	v_addc_co_u32_e32 v99, vcc, 0, v215, vcc
	global_load_dwordx4 v[174:177], v[98:99], off
	global_load_dwordx4 v[170:173], v[98:99], off offset:256
	v_add_co_u32_e32 v98, vcc, s0, v214
	s_mov_b32 s0, 0x80000
	s_nop 0
	v_addc_co_u32_e32 v99, vcc, 0, v215, vcc
	global_load_dwordx4 v[166:169], v[98:99], off
	global_load_dwordx4 v[162:165], v[98:99], off offset:256
	v_add_co_u32_e32 v98, vcc, s0, v214
	s_mov_b32 s0, 0x90000
	s_nop 0
	v_addc_co_u32_e32 v99, vcc, 0, v215, vcc
	global_load_dwordx4 v[158:161], v[98:99], off
	global_load_dwordx4 v[150:153], v[98:99], off offset:256
	v_add_co_u32_e32 v98, vcc, s0, v214
	s_mov_b32 s0, 0xa0000
	s_nop 0
	v_addc_co_u32_e32 v99, vcc, 0, v215, vcc
	global_load_dwordx4 v[142:145], v[98:99], off
	global_load_dwordx4 v[138:141], v[98:99], off offset:256
	v_add_co_u32_e32 v98, vcc, s0, v214
	s_mov_b32 s0, 0xb0000
	s_nop 0
	v_addc_co_u32_e32 v99, vcc, 0, v215, vcc
	global_load_dwordx4 v[126:129], v[98:99], off
	global_load_dwordx4 v[118:121], v[98:99], off offset:256
	v_add_co_u32_e32 v98, vcc, s0, v214
	v_xor_b32_e32 v228, 16, v220
	s_nop 0
	v_addc_co_u32_e32 v99, vcc, 0, v215, vcc
	global_load_dwordx4 v[106:109], v[98:99], off
	s_nop 0
	global_load_dwordx4 v[98:101], v[98:99], off offset:256
	v_add_u32_e32 v229, 64, v229
	v_cmp_lt_i32_e32 vcc, v228, v229
	s_lshl_b32 s66, s6, 2
	s_ashr_i32 s67, s66, 31
	v_cndmask_b32_e32 v228, v220, v228, vcc
	v_lshlrev_b32_e32 v235, 2, v228
	v_xor_b32_e32 v228, 32, v220
	v_cmp_lt_i32_e32 vcc, v228, v229
	s_waitcnt vmcnt(0) lgkmcnt(0)
	v_and_b32_e32 v229, 0xffff0000, v190
	v_cndmask_b32_e32 v228, v220, v228, vcc
	v_lshlrev_b32_e32 v236, 2, v228
	v_lshlrev_b32_e32 v228, 16, v190
	v_lshlrev_b32_e32 v190, 16, v191
	v_and_b32_e32 v191, 0xffff0000, v191
	v_pk_add_f32 v[154:155], v[154:155], v[228:229]
	v_pk_add_f32 v[156:157], v[156:157], v[190:191]
	v_cvt_pk_bf16_f32 v154, v154, v155
	v_cvt_pk_bf16_f32 v155, v156, v157
	v_lshlrev_b32_e32 v156, 16, v192
	v_and_b32_e32 v157, 0xffff0000, v192
	v_pk_add_f32 v[146:147], v[146:147], v[156:157]
	s_nop 0
	v_cvt_pk_bf16_f32 v156, v146, v147
	v_lshlrev_b32_e32 v146, 16, v193
	v_and_b32_e32 v147, 0xffff0000, v193
	v_pk_add_f32 v[146:147], v[148:149], v[146:147]
	v_and_b32_e32 v148, 0xffff0000, v155
	v_cvt_pk_bf16_f32 v157, v146, v147
	v_and_b32_e32 v147, 0xffff0000, v154
	v_lshlrev_b32_e32 v146, 16, v154
	v_mul_f32_e32 v147, v147, v147
	v_fmac_f32_e32 v147, v146, v146
	v_lshlrev_b32_e32 v146, 16, v155
	v_mul_f32_e32 v148, v148, v148
	v_fmac_f32_e32 v148, v146, v146
	v_add_f32_e32 v146, v147, v148
	v_and_b32_e32 v148, 0xffff0000, v156
	v_lshlrev_b32_e32 v147, 16, v156
	v_mul_f32_e32 v148, v148, v148
	v_fmac_f32_e32 v148, v147, v147
	v_add_f32_e32 v146, v148, v146
	v_and_b32_e32 v148, 0xffff0000, v157
	v_lshlrev_b32_e32 v147, 16, v157
	v_mul_f32_e32 v148, v148, v148
	v_fmac_f32_e32 v148, v147, v147
	v_add_f32_e32 v148, v148, v146
	v_lshlrev_b32_e32 v146, 16, v186
	v_and_b32_e32 v147, 0xffff0000, v186
	v_pk_add_f32 v[134:135], v[134:135], v[146:147]
	v_lshlrev_b32_e32 v146, 16, v187
	v_and_b32_e32 v147, 0xffff0000, v187
	v_pk_add_f32 v[136:137], v[136:137], v[146:147]
	v_cvt_pk_bf16_f32 v134, v134, v135
	v_cvt_pk_bf16_f32 v135, v136, v137
	v_lshlrev_b32_e32 v136, 16, v188
	v_and_b32_e32 v137, 0xffff0000, v188
	v_pk_add_f32 v[130:131], v[130:131], v[136:137]
	global_store_dwordx4 v[214:215], v[154:157], off
	v_cvt_pk_bf16_f32 v136, v130, v131
	v_lshlrev_b32_e32 v130, 16, v189
	v_and_b32_e32 v131, 0xffff0000, v189
	v_pk_add_f32 v[130:131], v[132:133], v[130:131]
	v_and_b32_e32 v132, 0xffff0000, v135
	v_cvt_pk_bf16_f32 v137, v130, v131
	v_and_b32_e32 v131, 0xffff0000, v134
	v_lshlrev_b32_e32 v130, 16, v134
	v_mul_f32_e32 v131, v131, v131
	v_fmac_f32_e32 v131, v130, v130
	v_add_f32_e32 v130, v131, v148
	v_lshlrev_b32_e32 v131, 16, v135
	v_mul_f32_e32 v132, v132, v132
	v_fmac_f32_e32 v132, v131, v131
	v_add_f32_e32 v130, v132, v130
	v_and_b32_e32 v132, 0xffff0000, v136
	v_lshlrev_b32_e32 v131, 16, v136
	v_mul_f32_e32 v132, v132, v132
	v_fmac_f32_e32 v132, v131, v131
	v_add_f32_e32 v130, v132, v130
	v_and_b32_e32 v132, 0xffff0000, v137
	v_lshlrev_b32_e32 v131, 16, v137
	v_mul_f32_e32 v132, v132, v132
	v_fmac_f32_e32 v132, v131, v131
	v_add_f32_e32 v130, v132, v130
	v_mov_b32_e32 v131, v130
	s_nop 1
	v_permlane16_swap_b32_e32 v130, v131
	global_store_dwordx4 v[214:215], v[134:137], off offset:256
	s_waitcnt lgkmcnt(0)
	v_add_f32_e32 v130, v130, v131
	v_mov_b32_e32 v131, v130
	s_nop 1
	v_permlane32_swap_b32_e32 v130, v131
	s_and_saveexec_b64 s[0:1], s[38:39]
	s_cbranch_execz .LBB0_452
	v_lshlrev_b64 v[132:133], 7, v[212:213]
	v_lshl_add_u64 v[132:133], s[44:45], 0, v[132:133]
	v_lshl_add_u64 v[132:133], s[66:67], 2, v[132:133]
	s_lshl_b32 s28, s47, 2
	v_lshl_add_u64 v[132:133], v[132:133], 0, s[28:29]
	s_waitcnt lgkmcnt(0)
	v_add_f32_e32 v130, v130, v131
	global_store_dword v[132:133], v130, off
; __device__ __forceinline__ unsigned pk_bf16(float lo, float hi) { f32x2e v = {lo, hi}; bf16x2e b = __builtin_convertvector(v, bf16x2e); return __builtin_bit_cast(unsigned, b); }
;     __device__ __forceinline__ void operator()(const f32x4 (&acc)[2][2][4][2], const Unit& u, int wr, int wc, int fr, int fq) const {
;     ...
;         for (int ai = 0; ai < 2; ++ai)
; #pragma unroll
;             for (int m = 0; m < 4; ++m) { const int row = u.pm * BM + ai * HALF + wr * 64 + m * 16 + fr; bf16_t* rowp = base + (size_t)(ai * HALF + m * 16) * ldc;
;                 float qs = 0.f;
; #pragma unroll
;                 for (int bj = 0; bj < 2; ++bj) { const f32x4 a0 = acc[ai][bj][m][0], a1 = acc[ai][bj][m][1]; const u32x4 q = r[ai][m][bj]; u32x4 w;
;                     w.x = pk_bf16(__uint_as_float(q.x << 16) + a0.x, __uint_as_float(q.x & 0xffff0000u) + a0.y);
;                     w.y = pk_bf16(__uint_as_float(q.y << 16) + a0.z, __uint_as_float(q.y & 0xffff0000u) + a0.w);
;                     w.z = pk_bf16(__uint_as_float(q.z << 16) + a1.x, __uint_as_float(q.z & 0xffff0000u) + a1.y);
;                     w.w = pk_bf16(__uint_as_float(q.w << 16) + a1.z, __uint_as_float(q.w & 0xffff0000u) + a1.w);
;                     *(u32x4*)(rowp + bj * HALF) = w;
; #pragma unroll
;                     for (int e = 0; e < 4; ++e) { const float h0 = __uint_as_float(w[e] << 16), h1 = __uint_as_float(w[e] & 0xffff0000u); qs += h0 * h0 + h1 * h1; } }
;                 qs += __shfl_xor(qs, 16); qs += __shfl_xor(qs, 32);
;                 if (fq == 0) ss[(size_t)row * 32 + u.pn * 4 + wc] = qs; }
.LBB0_452:
	s_or_b64 exec, exec, s[0:1]
	v_lshlrev_b32_e32 v130, 16, v182
	s_waitcnt lgkmcnt(0)
	v_and_b32_e32 v131, 0xffff0000, v182
	v_pk_add_f32 v[122:123], v[122:123], v[130:131]
	v_lshlrev_b32_e32 v130, 16, v183
	v_and_b32_e32 v131, 0xffff0000, v183
	v_pk_add_f32 v[124:125], v[124:125], v[130:131]
	v_cvt_pk_bf16_f32 v122, v122, v123
	v_cvt_pk_bf16_f32 v123, v124, v125
	v_lshlrev_b32_e32 v124, 16, v184
	v_and_b32_e32 v125, 0xffff0000, v184
	v_pk_add_f32 v[114:115], v[114:115], v[124:125]
	s_mov_b64 s[0:1], 0x10000
	v_cvt_pk_bf16_f32 v124, v114, v115
	v_lshlrev_b32_e32 v114, 16, v185
	v_and_b32_e32 v115, 0xffff0000, v185
	v_pk_add_f32 v[114:115], v[116:117], v[114:115]
	v_and_b32_e32 v116, 0xffff0000, v123
	v_cvt_pk_bf16_f32 v125, v114, v115
	v_and_b32_e32 v115, 0xffff0000, v122
	v_lshlrev_b32_e32 v114, 16, v122
	v_mul_f32_e32 v115, v115, v115
	v_fmac_f32_e32 v115, v114, v114
	v_lshlrev_b32_e32 v114, 16, v123
	v_mul_f32_e32 v116, v116, v116
	v_fmac_f32_e32 v116, v114, v114
	v_add_f32_e32 v114, v115, v116
	v_and_b32_e32 v116, 0xffff0000, v124
	v_lshlrev_b32_e32 v115, 16, v124
	v_mul_f32_e32 v116, v116, v116
	v_fmac_f32_e32 v116, v115, v115
	v_add_f32_e32 v114, v116, v114
	v_and_b32_e32 v116, 0xffff0000, v125
	v_lshlrev_b32_e32 v115, 16, v125
	v_mul_f32_e32 v116, v116, v116
	v_fmac_f32_e32 v116, v115, v115
	v_add_f32_e32 v116, v116, v114
	v_lshlrev_b32_e32 v114, 16, v178
	v_and_b32_e32 v115, 0xffff0000, v178
	v_pk_add_f32 v[110:111], v[110:111], v[114:115]
	v_lshlrev_b32_e32 v114, 16, v179
	v_and_b32_e32 v115, 0xffff0000, v179
	v_pk_add_f32 v[112:113], v[112:113], v[114:115]
	v_cvt_pk_bf16_f32 v110, v110, v111
	v_cvt_pk_bf16_f32 v111, v112, v113
	v_lshlrev_b32_e32 v112, 16, v180
	v_and_b32_e32 v113, 0xffff0000, v180
	v_pk_add_f32 v[102:103], v[102:103], v[112:113]
	s_nop 0
	v_cvt_pk_bf16_f32 v112, v102, v103
	v_lshlrev_b32_e32 v102, 16, v181
	v_and_b32_e32 v103, 0xffff0000, v181
	v_pk_add_f32 v[102:103], v[104:105], v[102:103]
	v_and_b32_e32 v104, 0xffff0000, v111
	v_cvt_pk_bf16_f32 v113, v102, v103
	v_and_b32_e32 v103, 0xffff0000, v110
	v_lshlrev_b32_e32 v102, 16, v110
	v_mul_f32_e32 v103, v103, v103
	v_fmac_f32_e32 v103, v102, v102
	v_add_f32_e32 v102, v103, v116
	v_lshlrev_b32_e32 v103, 16, v111
	v_mul_f32_e32 v104, v104, v104
	v_fmac_f32_e32 v104, v103, v103
	v_add_f32_e32 v102, v104, v102
	v_and_b32_e32 v104, 0xffff0000, v112
	v_lshlrev_b32_e32 v103, 16, v112
	v_mul_f32_e32 v104, v104, v104
	v_fmac_f32_e32 v104, v103, v103
	v_add_f32_e32 v102, v104, v102
	v_and_b32_e32 v104, 0xffff0000, v113
	v_lshlrev_b32_e32 v103, 16, v113
	v_mul_f32_e32 v104, v104, v104
	v_fmac_f32_e32 v104, v103, v103
	v_add_f32_e32 v102, v104, v102
	v_mov_b32_e32 v103, v102
	s_nop 1
	v_permlane16_swap_b32_e32 v102, v103
	v_lshl_add_u64 v[104:105], v[214:215], 0, s[0:1]
	s_mov_b64 s[0:1], 0x10100
	v_lshl_add_u64 v[114:115], v[214:215], 0, s[0:1]
	global_store_dwordx4 v[104:105], v[122:125], off
	global_store_dwordx4 v[114:115], v[110:113], off
	s_waitcnt lgkmcnt(0)
	v_add_f32_e32 v102, v102, v103
	v_mov_b32_e32 v103, v102
	s_nop 1
	v_permlane32_swap_b32_e32 v102, v103
	s_and_saveexec_b64 s[0:1], s[38:39]
	s_cbranch_execz .LBB0_454
	v_or_b32_e32 v104, 16, v212
	v_ashrrev_i32_e32 v105, 31, v104
	s_waitcnt lgkmcnt(0)
	v_add_f32_e32 v110, v102, v103
	v_lshlrev_b64 v[102:103], 7, v[104:105]
	v_lshl_add_u64 v[102:103], s[44:45], 0, v[102:103]
	v_lshl_add_u64 v[102:103], s[66:67], 2, v[102:103]
	s_lshl_b32 s28, s47, 2
	v_lshl_add_u64 v[102:103], v[102:103], 0, s[28:29]
	global_store_dword v[102:103], v110, off
.LBB0_454:
	s_or_b64 exec, exec, s[0:1]
	v_lshlrev_b32_e32 v102, 16, v174
	s_waitcnt lgkmcnt(0)
	v_and_b32_e32 v103, 0xffff0000, v174
	v_pk_add_f32 v[92:93], v[92:93], v[102:103]
	v_lshlrev_b32_e32 v102, 16, v175
	v_and_b32_e32 v103, 0xffff0000, v175
	v_pk_add_f32 v[94:95], v[94:95], v[102:103]
	v_cvt_pk_bf16_f32 v92, v92, v93
	v_cvt_pk_bf16_f32 v93, v94, v95
	v_lshlrev_b32_e32 v94, 16, v176
	v_and_b32_e32 v95, 0xffff0000, v176
	v_pk_add_f32 v[88:89], v[88:89], v[94:95]
	s_mov_b64 s[0:1], 0x20000
	v_cvt_pk_bf16_f32 v94, v88, v89
	v_lshlrev_b32_e32 v88, 16, v177
	v_and_b32_e32 v89, 0xffff0000, v177
	v_pk_add_f32 v[88:89], v[90:91], v[88:89]
	v_and_b32_e32 v90, 0xffff0000, v93
	v_cvt_pk_bf16_f32 v95, v88, v89
	v_and_b32_e32 v89, 0xffff0000, v92
	v_lshlrev_b32_e32 v88, 16, v92
	v_mul_f32_e32 v89, v89, v89
	v_fmac_f32_e32 v89, v88, v88
	v_lshlrev_b32_e32 v88, 16, v93
	v_mul_f32_e32 v90, v90, v90
	v_fmac_f32_e32 v90, v88, v88
	v_add_f32_e32 v88, v89, v90
	v_and_b32_e32 v90, 0xffff0000, v94
	v_lshlrev_b32_e32 v89, 16, v94
	v_mul_f32_e32 v90, v90, v90
	v_fmac_f32_e32 v90, v89, v89
	v_add_f32_e32 v88, v90, v88
	v_and_b32_e32 v90, 0xffff0000, v95
	v_lshlrev_b32_e32 v89, 16, v95
	v_mul_f32_e32 v90, v90, v90
	v_fmac_f32_e32 v90, v89, v89
	v_add_f32_e32 v90, v90, v88
	v_lshlrev_b32_e32 v88, 16, v170
	v_and_b32_e32 v89, 0xffff0000, v170
	v_pk_add_f32 v[84:85], v[84:85], v[88:89]
	v_lshlrev_b32_e32 v88, 16, v171
	v_and_b32_e32 v89, 0xffff0000, v171
	v_pk_add_f32 v[86:87], v[86:87], v[88:89]
	v_cvt_pk_bf16_f32 v84, v84, v85
	v_cvt_pk_bf16_f32 v85, v86, v87
	v_lshlrev_b32_e32 v86, 16, v172
	v_and_b32_e32 v87, 0xffff0000, v172
	v_pk_add_f32 v[80:81], v[80:81], v[86:87]
	s_nop 0
	v_cvt_pk_bf16_f32 v86, v80, v81
	v_lshlrev_b32_e32 v80, 16, v173
	v_and_b32_e32 v81, 0xffff0000, v173
	v_pk_add_f32 v[80:81], v[82:83], v[80:81]
	v_and_b32_e32 v82, 0xffff0000, v85
	v_cvt_pk_bf16_f32 v87, v80, v81
	v_and_b32_e32 v81, 0xffff0000, v84
	v_lshlrev_b32_e32 v80, 16, v84
	v_mul_f32_e32 v81, v81, v81
	v_fmac_f32_e32 v81, v80, v80
	v_add_f32_e32 v80, v81, v90
	v_lshlrev_b32_e32 v81, 16, v85
	v_mul_f32_e32 v82, v82, v82
	v_fmac_f32_e32 v82, v81, v81
	v_add_f32_e32 v80, v82, v80
	v_and_b32_e32 v82, 0xffff0000, v86
	v_lshlrev_b32_e32 v81, 16, v86
	v_mul_f32_e32 v82, v82, v82
	v_fmac_f32_e32 v82, v81, v81
	v_add_f32_e32 v80, v82, v80
	v_and_b32_e32 v82, 0xffff0000, v87
	v_lshlrev_b32_e32 v81, 16, v87
	v_mul_f32_e32 v82, v82, v82
	v_fmac_f32_e32 v82, v81, v81
	v_add_f32_e32 v80, v82, v80
	v_mov_b32_e32 v81, v80
	s_nop 1
	v_permlane16_swap_b32_e32 v80, v81
	v_lshl_add_u64 v[82:83], v[214:215], 0, s[0:1]
	s_mov_b64 s[0:1], 0x20100
	v_lshl_add_u64 v[88:89], v[214:215], 0, s[0:1]
	global_store_dwordx4 v[82:83], v[92:95], off
	global_store_dwordx4 v[88:89], v[84:87], off
	s_waitcnt lgkmcnt(0)
	v_add_f32_e32 v80, v80, v81
	v_mov_b32_e32 v81, v80
	s_nop 1
	v_permlane32_swap_b32_e32 v80, v81
	s_and_saveexec_b64 s[0:1], s[38:39]
	s_cbranch_execz .LBB0_456
	v_or_b32_e32 v82, 32, v212
	v_ashrrev_i32_e32 v83, 31, v82
	s_waitcnt lgkmcnt(0)
	v_add_f32_e32 v84, v80, v81
	v_lshlrev_b64 v[80:81], 7, v[82:83]
	v_lshl_add_u64 v[80:81], s[44:45], 0, v[80:81]
	v_lshl_add_u64 v[80:81], s[66:67], 2, v[80:81]
	s_lshl_b32 s28, s47, 2
	v_lshl_add_u64 v[80:81], v[80:81], 0, s[28:29]
	global_store_dword v[80:81], v84, off
; __device__ __forceinline__ unsigned pk_bf16(float lo, float hi) { f32x2e v = {lo, hi}; bf16x2e b = __builtin_convertvector(v, bf16x2e); return __builtin_bit_cast(unsigned, b); }
;     __device__ __forceinline__ void operator()(const f32x4 (&acc)[2][2][4][2], const Unit& u, int wr, int wc, int fr, int fq) const {
;     ...
;         for (int ai = 0; ai < 2; ++ai)
; #pragma unroll
;             for (int m = 0; m < 4; ++m) { const int row = u.pm * BM + ai * HALF + wr * 64 + m * 16 + fr; bf16_t* rowp = base + (size_t)(ai * HALF + m * 16) * ldc;
;                 float qs = 0.f;
; #pragma unroll
;                 for (int bj = 0; bj < 2; ++bj) { const f32x4 a0 = acc[ai][bj][m][0], a1 = acc[ai][bj][m][1]; const u32x4 q = r[ai][m][bj]; u32x4 w;
;                     w.x = pk_bf16(__uint_as_float(q.x << 16) + a0.x, __uint_as_float(q.x & 0xffff0000u) + a0.y);
;                     w.y = pk_bf16(__uint_as_float(q.y << 16) + a0.z, __uint_as_float(q.y & 0xffff0000u) + a0.w);
;                     w.z = pk_bf16(__uint_as_float(q.z << 16) + a1.x, __uint_as_float(q.z & 0xffff0000u) + a1.y);
;                     w.w = pk_bf16(__uint_as_float(q.w << 16) + a1.z, __uint_as_float(q.w & 0xffff0000u) + a1.w);
;                     *(u32x4*)(rowp + bj * HALF) = w;
; #pragma unroll
;                     for (int e = 0; e < 4; ++e) { const float h0 = __uint_as_float(w[e] << 16), h1 = __uint_as_float(w[e] & 0xffff0000u); qs += h0 * h0 + h1 * h1; } }
;                 qs += __shfl_xor(qs, 16); qs += __shfl_xor(qs, 32);
;                 if (fq == 0) ss[(size_t)row * 32 + u.pn * 4 + wc] = qs; }
.LBB0_456:
	s_or_b64 exec, exec, s[0:1]
	v_lshlrev_b32_e32 v80, 16, v166
	s_waitcnt lgkmcnt(0)
	v_and_b32_e32 v81, 0xffff0000, v166
	v_pk_add_f32 v[76:77], v[76:77], v[80:81]
	v_lshlrev_b32_e32 v80, 16, v167
	v_and_b32_e32 v81, 0xffff0000, v167
	v_pk_add_f32 v[78:79], v[78:79], v[80:81]
	v_cvt_pk_bf16_f32 v76, v76, v77
	v_cvt_pk_bf16_f32 v77, v78, v79
	v_lshlrev_b32_e32 v78, 16, v168
	v_and_b32_e32 v79, 0xffff0000, v168
	v_pk_add_f32 v[72:73], v[72:73], v[78:79]
	s_mov_b64 s[0:1], 0x30000
	v_cvt_pk_bf16_f32 v78, v72, v73
	v_lshlrev_b32_e32 v72, 16, v169
	v_and_b32_e32 v73, 0xffff0000, v169
	v_pk_add_f32 v[72:73], v[74:75], v[72:73]
	v_and_b32_e32 v74, 0xffff0000, v77
	v_cvt_pk_bf16_f32 v79, v72, v73
	v_and_b32_e32 v73, 0xffff0000, v76
	v_lshlrev_b32_e32 v72, 16, v76
	v_mul_f32_e32 v73, v73, v73
	v_fmac_f32_e32 v73, v72, v72
	v_lshlrev_b32_e32 v72, 16, v77
	v_mul_f32_e32 v74, v74, v74
	v_fmac_f32_e32 v74, v72, v72
	v_add_f32_e32 v72, v73, v74
	v_and_b32_e32 v74, 0xffff0000, v78
	v_lshlrev_b32_e32 v73, 16, v78
	v_mul_f32_e32 v74, v74, v74
	v_fmac_f32_e32 v74, v73, v73
	v_add_f32_e32 v72, v74, v72
	v_and_b32_e32 v74, 0xffff0000, v79
	v_lshlrev_b32_e32 v73, 16, v79
	v_mul_f32_e32 v74, v74, v74
	v_fmac_f32_e32 v74, v73, v73
	v_add_f32_e32 v74, v74, v72
	v_lshlrev_b32_e32 v72, 16, v162
	v_and_b32_e32 v73, 0xffff0000, v162
	v_pk_add_f32 v[68:69], v[68:69], v[72:73]
	v_lshlrev_b32_e32 v72, 16, v163
	v_and_b32_e32 v73, 0xffff0000, v163
	v_pk_add_f32 v[70:71], v[70:71], v[72:73]
	v_cvt_pk_bf16_f32 v68, v68, v69
	v_cvt_pk_bf16_f32 v69, v70, v71
	v_lshlrev_b32_e32 v70, 16, v164
	v_and_b32_e32 v71, 0xffff0000, v164
	v_pk_add_f32 v[64:65], v[64:65], v[70:71]
	s_nop 0
	v_cvt_pk_bf16_f32 v70, v64, v65
	v_lshlrev_b32_e32 v64, 16, v165
	v_and_b32_e32 v65, 0xffff0000, v165
	v_pk_add_f32 v[64:65], v[66:67], v[64:65]
	v_and_b32_e32 v66, 0xffff0000, v69
	v_cvt_pk_bf16_f32 v71, v64, v65
	v_and_b32_e32 v65, 0xffff0000, v68
	v_lshlrev_b32_e32 v64, 16, v68
	v_mul_f32_e32 v65, v65, v65
	v_fmac_f32_e32 v65, v64, v64
	v_add_f32_e32 v64, v65, v74
	v_lshlrev_b32_e32 v65, 16, v69
	v_mul_f32_e32 v66, v66, v66
	v_fmac_f32_e32 v66, v65, v65
	v_add_f32_e32 v64, v66, v64
	v_and_b32_e32 v66, 0xffff0000, v70
	v_lshlrev_b32_e32 v65, 16, v70
	v_mul_f32_e32 v66, v66, v66
	v_fmac_f32_e32 v66, v65, v65
	v_add_f32_e32 v64, v66, v64
	v_and_b32_e32 v66, 0xffff0000, v71
	v_lshlrev_b32_e32 v65, 16, v71
	v_mul_f32_e32 v66, v66, v66
	v_fmac_f32_e32 v66, v65, v65
	v_add_f32_e32 v64, v66, v64
	v_mov_b32_e32 v65, v64
	s_nop 1
	v_permlane16_swap_b32_e32 v64, v65
	v_lshl_add_u64 v[66:67], v[214:215], 0, s[0:1]
	s_mov_b64 s[0:1], 0x30100
	v_lshl_add_u64 v[72:73], v[214:215], 0, s[0:1]
	global_store_dwordx4 v[66:67], v[76:79], off
	global_store_dwordx4 v[72:73], v[68:71], off
	s_waitcnt lgkmcnt(0)
	v_add_f32_e32 v64, v64, v65
	v_mov_b32_e32 v65, v64
	s_nop 1
	v_permlane32_swap_b32_e32 v64, v65
	s_and_saveexec_b64 s[0:1], s[38:39]
	s_cbranch_execz .LBB0_458
	v_or_b32_e32 v66, 48, v212
	v_ashrrev_i32_e32 v67, 31, v66
	s_waitcnt lgkmcnt(0)
	v_add_f32_e32 v68, v64, v65
	v_lshlrev_b64 v[64:65], 7, v[66:67]
	v_lshl_add_u64 v[64:65], s[44:45], 0, v[64:65]
	v_lshl_add_u64 v[64:65], s[66:67], 2, v[64:65]
	s_lshl_b32 s28, s47, 2
	v_lshl_add_u64 v[64:65], v[64:65], 0, s[28:29]
	global_store_dword v[64:65], v68, off
.LBB0_458:
	s_or_b64 exec, exec, s[0:1]
	v_lshlrev_b32_e32 v64, 16, v158
	s_waitcnt lgkmcnt(0)
	v_and_b32_e32 v65, 0xffff0000, v158
	v_pk_add_f32 v[60:61], v[60:61], v[64:65]
	v_lshlrev_b32_e32 v64, 16, v159
	v_and_b32_e32 v65, 0xffff0000, v159
	v_pk_add_f32 v[62:63], v[62:63], v[64:65]
	v_cvt_pk_bf16_f32 v60, v60, v61
	v_cvt_pk_bf16_f32 v61, v62, v63
	v_lshlrev_b32_e32 v62, 16, v160
	v_and_b32_e32 v63, 0xffff0000, v160
	v_pk_add_f32 v[56:57], v[56:57], v[62:63]
	s_mov_b64 s[0:1], 0x80000
	v_cvt_pk_bf16_f32 v62, v56, v57
	v_lshlrev_b32_e32 v56, 16, v161
	v_and_b32_e32 v57, 0xffff0000, v161
	v_pk_add_f32 v[56:57], v[58:59], v[56:57]
	v_and_b32_e32 v58, 0xffff0000, v61
	v_cvt_pk_bf16_f32 v63, v56, v57
	v_and_b32_e32 v57, 0xffff0000, v60
	v_lshlrev_b32_e32 v56, 16, v60
	v_mul_f32_e32 v57, v57, v57
	v_fmac_f32_e32 v57, v56, v56
	v_lshlrev_b32_e32 v56, 16, v61
	v_mul_f32_e32 v58, v58, v58
	v_fmac_f32_e32 v58, v56, v56
	v_add_f32_e32 v56, v57, v58
	v_and_b32_e32 v58, 0xffff0000, v62
	v_lshlrev_b32_e32 v57, 16, v62
	v_mul_f32_e32 v58, v58, v58
	v_fmac_f32_e32 v58, v57, v57
	v_add_f32_e32 v56, v58, v56
	v_and_b32_e32 v58, 0xffff0000, v63
	v_lshlrev_b32_e32 v57, 16, v63
	v_mul_f32_e32 v58, v58, v58
	v_fmac_f32_e32 v58, v57, v57
	v_add_f32_e32 v58, v58, v56
	v_lshlrev_b32_e32 v56, 16, v150
	v_and_b32_e32 v57, 0xffff0000, v150
	v_pk_add_f32 v[52:53], v[52:53], v[56:57]
	v_lshlrev_b32_e32 v56, 16, v151
	v_and_b32_e32 v57, 0xffff0000, v151
	v_pk_add_f32 v[54:55], v[54:55], v[56:57]
	v_cvt_pk_bf16_f32 v52, v52, v53
	v_cvt_pk_bf16_f32 v53, v54, v55
	v_lshlrev_b32_e32 v54, 16, v152
	v_and_b32_e32 v55, 0xffff0000, v152
	v_pk_add_f32 v[48:49], v[48:49], v[54:55]
	s_nop 0
	v_cvt_pk_bf16_f32 v54, v48, v49
	v_lshlrev_b32_e32 v48, 16, v153
	v_and_b32_e32 v49, 0xffff0000, v153
	v_pk_add_f32 v[48:49], v[50:51], v[48:49]
	v_and_b32_e32 v50, 0xffff0000, v53
	v_cvt_pk_bf16_f32 v55, v48, v49
	v_and_b32_e32 v49, 0xffff0000, v52
	v_lshlrev_b32_e32 v48, 16, v52
	v_mul_f32_e32 v49, v49, v49
	v_fmac_f32_e32 v49, v48, v48
	v_add_f32_e32 v48, v49, v58
	v_lshlrev_b32_e32 v49, 16, v53
	v_mul_f32_e32 v50, v50, v50
	v_fmac_f32_e32 v50, v49, v49
	v_add_f32_e32 v48, v50, v48
	v_and_b32_e32 v50, 0xffff0000, v54
	v_lshlrev_b32_e32 v49, 16, v54
	v_mul_f32_e32 v50, v50, v50
	v_fmac_f32_e32 v50, v49, v49
	v_add_f32_e32 v48, v50, v48
	v_and_b32_e32 v50, 0xffff0000, v55
	v_lshlrev_b32_e32 v49, 16, v55
	v_mul_f32_e32 v50, v50, v50
	v_fmac_f32_e32 v50, v49, v49
	v_add_f32_e32 v48, v50, v48
	v_mov_b32_e32 v49, v48
	s_nop 1
	v_permlane16_swap_b32_e32 v48, v49
	v_lshl_add_u64 v[50:51], v[214:215], 0, s[0:1]
	s_mov_b64 s[0:1], 0x80100
	v_lshl_add_u64 v[56:57], v[214:215], 0, s[0:1]
	global_store_dwordx4 v[50:51], v[60:63], off
	global_store_dwordx4 v[56:57], v[52:55], off
	s_waitcnt lgkmcnt(0)
	v_add_f32_e32 v48, v48, v49
	v_mov_b32_e32 v49, v48
	s_nop 1
	v_permlane32_swap_b32_e32 v48, v49
	s_and_saveexec_b64 s[0:1], s[38:39]
	s_cbranch_execz .LBB0_460
	v_add_u32_e32 v50, 0x80, v212
	v_ashrrev_i32_e32 v51, 31, v50
	s_waitcnt lgkmcnt(0)
	v_add_f32_e32 v52, v48, v49
	v_lshlrev_b64 v[48:49], 7, v[50:51]
	v_lshl_add_u64 v[48:49], s[44:45], 0, v[48:49]
	v_lshl_add_u64 v[48:49], s[66:67], 2, v[48:49]
	s_lshl_b32 s28, s47, 2
	v_lshl_add_u64 v[48:49], v[48:49], 0, s[28:29]
	global_store_dword v[48:49], v52, off
; __device__ __forceinline__ unsigned pk_bf16(float lo, float hi) { f32x2e v = {lo, hi}; bf16x2e b = __builtin_convertvector(v, bf16x2e); return __builtin_bit_cast(unsigned, b); }
;     __device__ __forceinline__ void operator()(const f32x4 (&acc)[2][2][4][2], const Unit& u, int wr, int wc, int fr, int fq) const {
;     ...
;         for (int ai = 0; ai < 2; ++ai)
; #pragma unroll
;             for (int m = 0; m < 4; ++m) { const int row = u.pm * BM + ai * HALF + wr * 64 + m * 16 + fr; bf16_t* rowp = base + (size_t)(ai * HALF + m * 16) * ldc;
;                 float qs = 0.f;
; #pragma unroll
;                 for (int bj = 0; bj < 2; ++bj) { const f32x4 a0 = acc[ai][bj][m][0], a1 = acc[ai][bj][m][1]; const u32x4 q = r[ai][m][bj]; u32x4 w;
;                     w.x = pk_bf16(__uint_as_float(q.x << 16) + a0.x, __uint_as_float(q.x & 0xffff0000u) + a0.y);
;                     w.y = pk_bf16(__uint_as_float(q.y << 16) + a0.z, __uint_as_float(q.y & 0xffff0000u) + a0.w);
;                     w.z = pk_bf16(__uint_as_float(q.z << 16) + a1.x, __uint_as_float(q.z & 0xffff0000u) + a1.y);
;                     w.w = pk_bf16(__uint_as_float(q.w << 16) + a1.z, __uint_as_float(q.w & 0xffff0000u) + a1.w);
;                     *(u32x4*)(rowp + bj * HALF) = w;
; #pragma unroll
;                     for (int e = 0; e < 4; ++e) { const float h0 = __uint_as_float(w[e] << 16), h1 = __uint_as_float(w[e] & 0xffff0000u); qs += h0 * h0 + h1 * h1; } }
;                 qs += __shfl_xor(qs, 16); qs += __shfl_xor(qs, 32);
;                 if (fq == 0) ss[(size_t)row * 32 + u.pn * 4 + wc] = qs; }
.LBB0_460:
	s_or_b64 exec, exec, s[0:1]
	v_lshlrev_b32_e32 v48, 16, v142
	s_waitcnt lgkmcnt(0)
	v_and_b32_e32 v49, 0xffff0000, v142
	v_pk_add_f32 v[44:45], v[44:45], v[48:49]
	v_lshlrev_b32_e32 v48, 16, v143
	v_and_b32_e32 v49, 0xffff0000, v143
	v_pk_add_f32 v[46:47], v[46:47], v[48:49]
	v_cvt_pk_bf16_f32 v44, v44, v45
	v_cvt_pk_bf16_f32 v45, v46, v47
	v_lshlrev_b32_e32 v46, 16, v144
	v_and_b32_e32 v47, 0xffff0000, v144
	v_pk_add_f32 v[40:41], v[40:41], v[46:47]
	s_mov_b64 s[0:1], 0x90000
	v_cvt_pk_bf16_f32 v46, v40, v41
	v_lshlrev_b32_e32 v40, 16, v145
	v_and_b32_e32 v41, 0xffff0000, v145
	v_pk_add_f32 v[40:41], v[42:43], v[40:41]
	v_and_b32_e32 v42, 0xffff0000, v45
	v_cvt_pk_bf16_f32 v47, v40, v41
	v_and_b32_e32 v41, 0xffff0000, v44
	v_lshlrev_b32_e32 v40, 16, v44
	v_mul_f32_e32 v41, v41, v41
	v_fmac_f32_e32 v41, v40, v40
	v_lshlrev_b32_e32 v40, 16, v45
	v_mul_f32_e32 v42, v42, v42
	v_fmac_f32_e32 v42, v40, v40
	v_add_f32_e32 v40, v41, v42
	v_and_b32_e32 v42, 0xffff0000, v46
	v_lshlrev_b32_e32 v41, 16, v46
	v_mul_f32_e32 v42, v42, v42
	v_fmac_f32_e32 v42, v41, v41
	v_add_f32_e32 v40, v42, v40
	v_and_b32_e32 v42, 0xffff0000, v47
	v_lshlrev_b32_e32 v41, 16, v47
	v_mul_f32_e32 v42, v42, v42
	v_fmac_f32_e32 v42, v41, v41
	v_add_f32_e32 v42, v42, v40
	v_lshlrev_b32_e32 v40, 16, v138
	v_and_b32_e32 v41, 0xffff0000, v138
	v_pk_add_f32 v[36:37], v[36:37], v[40:41]
	v_lshlrev_b32_e32 v40, 16, v139
	v_and_b32_e32 v41, 0xffff0000, v139
	v_pk_add_f32 v[38:39], v[38:39], v[40:41]
	v_cvt_pk_bf16_f32 v36, v36, v37
	v_cvt_pk_bf16_f32 v37, v38, v39
	v_lshlrev_b32_e32 v38, 16, v140
	v_and_b32_e32 v39, 0xffff0000, v140
	v_pk_add_f32 v[32:33], v[32:33], v[38:39]
	s_nop 0
	v_cvt_pk_bf16_f32 v38, v32, v33
	v_lshlrev_b32_e32 v32, 16, v141
	v_and_b32_e32 v33, 0xffff0000, v141
	v_pk_add_f32 v[32:33], v[34:35], v[32:33]
	v_and_b32_e32 v34, 0xffff0000, v37
	v_cvt_pk_bf16_f32 v39, v32, v33
	v_and_b32_e32 v33, 0xffff0000, v36
	v_lshlrev_b32_e32 v32, 16, v36
	v_mul_f32_e32 v33, v33, v33
	v_fmac_f32_e32 v33, v32, v32
	v_add_f32_e32 v32, v33, v42
	v_lshlrev_b32_e32 v33, 16, v37
	v_mul_f32_e32 v34, v34, v34
	v_fmac_f32_e32 v34, v33, v33
	v_add_f32_e32 v32, v34, v32
	v_and_b32_e32 v34, 0xffff0000, v38
	v_lshlrev_b32_e32 v33, 16, v38
	v_mul_f32_e32 v34, v34, v34
	v_fmac_f32_e32 v34, v33, v33
	v_add_f32_e32 v32, v34, v32
	v_and_b32_e32 v34, 0xffff0000, v39
	v_lshlrev_b32_e32 v33, 16, v39
	v_mul_f32_e32 v34, v34, v34
	v_fmac_f32_e32 v34, v33, v33
	v_add_f32_e32 v32, v34, v32
	v_mov_b32_e32 v33, v32
	s_nop 1
	v_permlane16_swap_b32_e32 v32, v33
	v_lshl_add_u64 v[34:35], v[214:215], 0, s[0:1]
	s_mov_b64 s[0:1], 0x90100
	v_lshl_add_u64 v[40:41], v[214:215], 0, s[0:1]
	global_store_dwordx4 v[34:35], v[44:47], off
	global_store_dwordx4 v[40:41], v[36:39], off
	s_waitcnt lgkmcnt(0)
	v_add_f32_e32 v32, v32, v33
	v_mov_b32_e32 v33, v32
	s_nop 1
	v_permlane32_swap_b32_e32 v32, v33
	s_and_saveexec_b64 s[0:1], s[38:39]
	s_cbranch_execz .LBB0_462
	v_add_u32_e32 v34, 0x90, v212
	v_ashrrev_i32_e32 v35, 31, v34
	s_waitcnt lgkmcnt(0)
	v_add_f32_e32 v36, v32, v33
	v_lshlrev_b64 v[32:33], 7, v[34:35]
	v_lshl_add_u64 v[32:33], s[44:45], 0, v[32:33]
	v_lshl_add_u64 v[32:33], s[66:67], 2, v[32:33]
	s_lshl_b32 s28, s47, 2
	v_lshl_add_u64 v[32:33], v[32:33], 0, s[28:29]
	global_store_dword v[32:33], v36, off
; __device__ __forceinline__ unsigned pk_bf16(float lo, float hi) { f32x2e v = {lo, hi}; bf16x2e b = __builtin_convertvector(v, bf16x2e); return __builtin_bit_cast(unsigned, b); }
;     __device__ __forceinline__ void operator()(const f32x4 (&acc)[2][2][4][2], const Unit& u, int wr, int wc, int fr, int fq) const {
;     ...
;         for (int ai = 0; ai < 2; ++ai)
; #pragma unroll
;             for (int m = 0; m < 4; ++m) { const int row = u.pm * BM + ai * HALF + wr * 64 + m * 16 + fr; bf16_t* rowp = base + (size_t)(ai * HALF + m * 16) * ldc;
;                 float qs = 0.f;
; #pragma unroll
;                 for (int bj = 0; bj < 2; ++bj) { const f32x4 a0 = acc[ai][bj][m][0], a1 = acc[ai][bj][m][1]; const u32x4 q = r[ai][m][bj]; u32x4 w;
;                     w.x = pk_bf16(__uint_as_float(q.x << 16) + a0.x, __uint_as_float(q.x & 0xffff0000u) + a0.y);
;                     w.y = pk_bf16(__uint_as_float(q.y << 16) + a0.z, __uint_as_float(q.y & 0xffff0000u) + a0.w);
;                     w.z = pk_bf16(__uint_as_float(q.z << 16) + a1.x, __uint_as_float(q.z & 0xffff0000u) + a1.y);
;                     w.w = pk_bf16(__uint_as_float(q.w << 16) + a1.z, __uint_as_float(q.w & 0xffff0000u) + a1.w);
;                     *(u32x4*)(rowp + bj * HALF) = w;
; #pragma unroll
;                     for (int e = 0; e < 4; ++e) { const float h0 = __uint_as_float(w[e] << 16), h1 = __uint_as_float(w[e] & 0xffff0000u); qs += h0 * h0 + h1 * h1; } }
;                 qs += __shfl_xor(qs, 16); qs += __shfl_xor(qs, 32);
;                 if (fq == 0) ss[(size_t)row * 32 + u.pn * 4 + wc] = qs; }
.LBB0_462:
	s_or_b64 exec, exec, s[0:1]
	v_lshlrev_b32_e32 v32, 16, v126
	s_waitcnt lgkmcnt(0)
	v_and_b32_e32 v33, 0xffff0000, v126
	v_pk_add_f32 v[28:29], v[28:29], v[32:33]
	v_lshlrev_b32_e32 v32, 16, v127
	v_and_b32_e32 v33, 0xffff0000, v127
	v_pk_add_f32 v[30:31], v[30:31], v[32:33]
	v_cvt_pk_bf16_f32 v28, v28, v29
	v_cvt_pk_bf16_f32 v29, v30, v31
	v_lshlrev_b32_e32 v30, 16, v128
	v_and_b32_e32 v31, 0xffff0000, v128
	v_pk_add_f32 v[24:25], v[24:25], v[30:31]
	s_mov_b64 s[0:1], 0xa0000
	v_cvt_pk_bf16_f32 v30, v24, v25
	v_lshlrev_b32_e32 v24, 16, v129
	v_and_b32_e32 v25, 0xffff0000, v129
	v_pk_add_f32 v[24:25], v[26:27], v[24:25]
	v_and_b32_e32 v26, 0xffff0000, v29
	v_cvt_pk_bf16_f32 v31, v24, v25
	v_and_b32_e32 v25, 0xffff0000, v28
	v_lshlrev_b32_e32 v24, 16, v28
	v_mul_f32_e32 v25, v25, v25
	v_fmac_f32_e32 v25, v24, v24
	v_lshlrev_b32_e32 v24, 16, v29
	v_mul_f32_e32 v26, v26, v26
	v_fmac_f32_e32 v26, v24, v24
	v_add_f32_e32 v24, v25, v26
	v_and_b32_e32 v26, 0xffff0000, v30
	v_lshlrev_b32_e32 v25, 16, v30
	v_mul_f32_e32 v26, v26, v26
	v_fmac_f32_e32 v26, v25, v25
	v_add_f32_e32 v24, v26, v24
	v_and_b32_e32 v26, 0xffff0000, v31
	v_lshlrev_b32_e32 v25, 16, v31
	v_mul_f32_e32 v26, v26, v26
	v_fmac_f32_e32 v26, v25, v25
	v_add_f32_e32 v26, v26, v24
	v_lshlrev_b32_e32 v24, 16, v118
	v_and_b32_e32 v25, 0xffff0000, v118
	v_pk_add_f32 v[20:21], v[20:21], v[24:25]
	v_lshlrev_b32_e32 v24, 16, v119
	v_and_b32_e32 v25, 0xffff0000, v119
	v_pk_add_f32 v[22:23], v[22:23], v[24:25]
	v_cvt_pk_bf16_f32 v20, v20, v21
	v_cvt_pk_bf16_f32 v21, v22, v23
	v_lshlrev_b32_e32 v22, 16, v120
	v_and_b32_e32 v23, 0xffff0000, v120
	v_pk_add_f32 v[16:17], v[16:17], v[22:23]
	s_nop 0
	v_cvt_pk_bf16_f32 v22, v16, v17
	v_lshlrev_b32_e32 v16, 16, v121
	v_and_b32_e32 v17, 0xffff0000, v121
	v_pk_add_f32 v[16:17], v[18:19], v[16:17]
	v_and_b32_e32 v18, 0xffff0000, v21
	v_cvt_pk_bf16_f32 v23, v16, v17
	v_and_b32_e32 v17, 0xffff0000, v20
	v_lshlrev_b32_e32 v16, 16, v20
	v_mul_f32_e32 v17, v17, v17
	v_fmac_f32_e32 v17, v16, v16
	v_add_f32_e32 v16, v17, v26
	v_lshlrev_b32_e32 v17, 16, v21
	v_mul_f32_e32 v18, v18, v18
	v_fmac_f32_e32 v18, v17, v17
	v_add_f32_e32 v16, v18, v16
	v_and_b32_e32 v18, 0xffff0000, v22
	v_lshlrev_b32_e32 v17, 16, v22
	v_mul_f32_e32 v18, v18, v18
	v_fmac_f32_e32 v18, v17, v17
	v_add_f32_e32 v16, v18, v16
	v_and_b32_e32 v18, 0xffff0000, v23
	v_lshlrev_b32_e32 v17, 16, v23
	v_mul_f32_e32 v18, v18, v18
	v_fmac_f32_e32 v18, v17, v17
	v_add_f32_e32 v16, v18, v16
	v_mov_b32_e32 v17, v16
	s_nop 1
	v_permlane16_swap_b32_e32 v16, v17
	v_lshl_add_u64 v[18:19], v[214:215], 0, s[0:1]
	s_mov_b64 s[0:1], 0xa0100
	v_lshl_add_u64 v[24:25], v[214:215], 0, s[0:1]
	global_store_dwordx4 v[18:19], v[28:31], off
	global_store_dwordx4 v[24:25], v[20:23], off
	s_waitcnt lgkmcnt(0)
	v_add_f32_e32 v16, v16, v17
	v_mov_b32_e32 v17, v16
	s_nop 1
	v_permlane32_swap_b32_e32 v16, v17
	s_and_saveexec_b64 s[0:1], s[38:39]
	s_cbranch_execz .LBB0_464
	v_add_u32_e32 v18, 0xa0, v212
	v_ashrrev_i32_e32 v19, 31, v18
	s_waitcnt lgkmcnt(0)
	v_add_f32_e32 v20, v16, v17
	v_lshlrev_b64 v[16:17], 7, v[18:19]
	v_lshl_add_u64 v[16:17], s[44:45], 0, v[16:17]
	v_lshl_add_u64 v[16:17], s[66:67], 2, v[16:17]
	s_lshl_b32 s28, s47, 2
	v_lshl_add_u64 v[16:17], v[16:17], 0, s[28:29]
	global_store_dword v[16:17], v20, off
.LBB0_464:
	s_or_b64 exec, exec, s[0:1]
	v_lshlrev_b32_e32 v16, 16, v106
	s_waitcnt lgkmcnt(0)
	v_and_b32_e32 v17, 0xffff0000, v106
	v_pk_add_f32 v[12:13], v[12:13], v[16:17]
	v_lshlrev_b32_e32 v16, 16, v107
	v_and_b32_e32 v17, 0xffff0000, v107
	v_pk_add_f32 v[14:15], v[14:15], v[16:17]
	v_cvt_pk_bf16_f32 v12, v12, v13
	v_cvt_pk_bf16_f32 v13, v14, v15
	v_lshlrev_b32_e32 v14, 16, v108
	v_and_b32_e32 v15, 0xffff0000, v108
	v_pk_add_f32 v[8:9], v[8:9], v[14:15]
	s_mov_b64 s[0:1], 0xb0000
	v_cvt_pk_bf16_f32 v14, v8, v9
	v_lshlrev_b32_e32 v8, 16, v109
	v_and_b32_e32 v9, 0xffff0000, v109
	v_pk_add_f32 v[8:9], v[10:11], v[8:9]
	v_and_b32_e32 v10, 0xffff0000, v13
	v_cvt_pk_bf16_f32 v15, v8, v9
	v_and_b32_e32 v9, 0xffff0000, v12
	v_lshlrev_b32_e32 v8, 16, v12
	v_mul_f32_e32 v9, v9, v9
	v_fmac_f32_e32 v9, v8, v8
	v_lshlrev_b32_e32 v8, 16, v13
	v_mul_f32_e32 v10, v10, v10
	v_fmac_f32_e32 v10, v8, v8
	v_add_f32_e32 v8, v9, v10
	v_and_b32_e32 v10, 0xffff0000, v14
	v_lshlrev_b32_e32 v9, 16, v14
	v_mul_f32_e32 v10, v10, v10
	v_fmac_f32_e32 v10, v9, v9
	v_add_f32_e32 v8, v10, v8
	v_and_b32_e32 v10, 0xffff0000, v15
	v_lshlrev_b32_e32 v9, 16, v15
	v_mul_f32_e32 v10, v10, v10
	v_fmac_f32_e32 v10, v9, v9
	v_add_f32_e32 v10, v10, v8
	v_lshlrev_b32_e32 v8, 16, v98
	v_and_b32_e32 v9, 0xffff0000, v98
	v_pk_add_f32 v[4:5], v[4:5], v[8:9]
	v_lshlrev_b32_e32 v8, 16, v99
	v_and_b32_e32 v9, 0xffff0000, v99
	v_pk_add_f32 v[6:7], v[6:7], v[8:9]
	v_cvt_pk_bf16_f32 v4, v4, v5
	v_cvt_pk_bf16_f32 v5, v6, v7
	v_lshlrev_b32_e32 v6, 16, v100
	v_and_b32_e32 v7, 0xffff0000, v100
	v_pk_add_f32 v[0:1], v[0:1], v[6:7]
	s_nop 0
	v_cvt_pk_bf16_f32 v6, v0, v1
	v_lshlrev_b32_e32 v0, 16, v101
	v_and_b32_e32 v1, 0xffff0000, v101
	v_pk_add_f32 v[0:1], v[2:3], v[0:1]
	v_and_b32_e32 v2, 0xffff0000, v5
	v_cvt_pk_bf16_f32 v7, v0, v1
	v_and_b32_e32 v1, 0xffff0000, v4
	v_lshlrev_b32_e32 v0, 16, v4
	v_mul_f32_e32 v1, v1, v1
	v_fmac_f32_e32 v1, v0, v0
	v_add_f32_e32 v0, v1, v10
	v_lshlrev_b32_e32 v1, 16, v5
	v_mul_f32_e32 v2, v2, v2
	v_fmac_f32_e32 v2, v1, v1
	v_add_f32_e32 v0, v2, v0
	v_and_b32_e32 v2, 0xffff0000, v6
	v_lshlrev_b32_e32 v1, 16, v6
	v_mul_f32_e32 v2, v2, v2
	v_fmac_f32_e32 v2, v1, v1
	v_add_f32_e32 v0, v2, v0
	v_and_b32_e32 v2, 0xffff0000, v7
	v_lshlrev_b32_e32 v1, 16, v7
	v_mul_f32_e32 v2, v2, v2
	v_fmac_f32_e32 v2, v1, v1
	v_add_f32_e32 v0, v2, v0
	v_mov_b32_e32 v1, v0
	s_nop 1
	v_permlane16_swap_b32_e32 v0, v1
	v_lshl_add_u64 v[2:3], v[214:215], 0, s[0:1]
	s_mov_b64 s[0:1], 0xb0100
	v_lshl_add_u64 v[8:9], v[214:215], 0, s[0:1]
	global_store_dwordx4 v[2:3], v[12:15], off
	global_store_dwordx4 v[8:9], v[4:7], off
	s_waitcnt lgkmcnt(0)
	v_add_f32_e32 v0, v0, v1
	v_mov_b32_e32 v1, v0
	s_nop 1
	v_permlane32_swap_b32_e32 v0, v1
	s_and_saveexec_b64 s[0:1], s[38:39]
	s_cbranch_execz .LBB0_466
	v_add_u32_e32 v2, 0xb0, v212
	v_ashrrev_i32_e32 v3, 31, v2
	s_waitcnt lgkmcnt(0)
	v_add_f32_e32 v4, v0, v1
	v_lshlrev_b64 v[0:1], 7, v[2:3]
	v_lshl_add_u64 v[0:1], s[44:45], 0, v[0:1]
	v_lshl_add_u64 v[0:1], s[66:67], 2, v[0:1]
	s_lshl_b32 s28, s47, 2
	v_lshl_add_u64 v[0:1], v[0:1], 0, s[28:29]
	global_store_dword v[0:1], v4, off
